# phase-0 weight-transpose loop: top wait covers only the prefetch loads (vmcnt(2)), not the two just-issued tile stores
# speedup vs baseline: 1.0064x; 1.0064x over previous
; __device__ __forceinline__ void pro_a_phase(const Params& p, LAS unsigned char* lds) {
;     ...
;     auto decode = [&](int tt, const float*& src, bf16_t*& dst, int& K, int& N, int& mode, int& n0, int& k0) {
;         const int l = tt / 6144, u = tt % 6144; int v;
;         if (u < 1536) { mode = 2; K = DM; N = DIN; v = u; src = p.w_in + (size_t)l * DM * DIN; dst = (bf16_t*)(p.ws + WS_WT_IN) + (size_t)l * DIN * LDU; }
;         else if (u < 2048) { mode = 1; K = DM; N = DM; v = u - 1536; src = p.w_out + (size_t)l * DM * DM; dst = (bf16_t*)(p.ws + WS_WT_OUT) + (size_t)l * DM * LDU; }
;         else if (u < 4096) { mode = 1; K = DM; N = DFF; v = u - 2048; src = p.w_ff1 + (size_t)l * DM * DFF; dst = (bf16_t*)(p.ws + WS_WT_FF1) + (size_t)l * DFF * LDU; }
;         else { mode = 1; K = DFF; N = DM; v = u - 4096; src = p.w_ff2 + (size_t)l * DFF * DM; dst = (bf16_t*)(p.ws + WS_WT_FF2) + (size_t)l * DM * LDH; }
;         const int ntn = N >> 6, kt = v / ntn, nt = v % ntn;
;         src += (size_t)(kt * 128) * N + nt * 64; n0 = nt * 64; k0 = kt * 128;
;     };
;     ...
;     int tt = item - FIRST_TR;
;     if (tt < N_TR) {
;         const float* src; bf16_t* dst; int K, N, mode, n0, k0; decode(tt, src, dst, K, N, mode, n0, k0);
;         f32x4 rg[4];
; #pragma unroll
;         for (int i = 0; i < 4; ++i) rg[i] = __builtin_nontemporal_load((const f32x4*)(src + (size_t)(lk + 32 * i) * N + ln4 * 4));
.LBB0_358:
	s_lshr_b32 s6, s8, 6
	s_waitcnt vmcnt(0)
	v_cvt_f32_i32_e32 v0, s6
	s_sext_i32_i16 s2, s10
	v_cvt_f32_i32_e32 v1, s2
	s_ashr_i32 s2, s2, 30
	v_rcp_iflag_f32_e32 v2, v0
	s_or_b32 s7, s2, 1
	v_ashrrev_i32_e32 v20, 4, v48
	v_and_b32_e32 v17, 15, v48
	v_mul_f32_e32 v2, v1, v2
	v_trunc_f32_e32 v2, v2
	v_fma_f32 v1, -v2, v0, v1
	v_cvt_i32_f32_e32 v2, v2
	v_cmp_ge_f32_e64 s[2:3], |v1|, v0
	s_and_b64 s[2:3], s[2:3], exec
	s_cselect_b32 s2, s7, 0
	v_readfirstlane_b32 s3, v2
	s_add_i32 s2, s3, s2
	s_sext_i32_i16 s3, s2
	s_mul_i32 s2, s2, s6
	s_sub_i32 s2, s10, s2
	s_lshl_b32 s20, s3, 7
	s_ashr_i32 s3, s3, 31
	s_sext_i32_i16 s2, s2
	s_mul_i32 s3, s3, s8
	s_mul_hi_u32 s6, s20, s8
	s_add_i32 s7, s6, s3
	s_mul_i32 s6, s20, s8
	s_lshl_b32 s2, s2, 6
	s_ashr_i32 s3, s2, 31
	s_lshl_b64 s[6:7], s[6:7], 2
	s_add_u32 s6, s4, s6
	s_addc_u32 s7, s5, s7
	s_lshl_b64 s[4:5], s[2:3], 2
	s_add_u32 s4, s6, s4
	s_addc_u32 s5, s7, s5
	v_lshlrev_b32_e32 v152, 4, v17
	v_add_u32_e32 v24, 64, v20
	v_lshl_add_u64 v[8:9], s[4:5], 0, v[152:153]
	v_mad_u64_u32 v[0:1], s[4:5], s8, v20, 0
	v_mad_u64_u32 v[10:11], s[4:5], s8, v24, 0
	v_ashrrev_i32_e32 v21, 31, v20
	v_mov_b32_e32 v2, v1
	v_ashrrev_i32_e32 v25, 31, v24
	v_mov_b32_e32 v12, v11
	v_mad_u64_u32 v[2:3], s[4:5], s8, v21, v[2:3]
	v_add_u32_e32 v22, 32, v20
	v_mad_u64_u32 v[12:13], s[4:5], s8, v25, v[12:13]
	v_add_u32_e32 v26, 0x60, v20
	v_mov_b32_e32 v1, v2
	v_mad_u64_u32 v[2:3], s[4:5], s8, v22, 0
	v_mov_b32_e32 v11, v12
	v_mad_u64_u32 v[12:13], s[4:5], s8, v26, 0
	v_ashrrev_i32_e32 v23, 31, v22
	v_mov_b32_e32 v4, v3
	v_ashrrev_i32_e32 v27, 31, v26
	v_mov_b32_e32 v14, v13
	v_mad_u64_u32 v[4:5], s[4:5], s8, v23, v[4:5]
	v_mad_u64_u32 v[14:15], s[4:5], s8, v27, v[14:15]
	v_mov_b32_e32 v3, v4
	v_mov_b32_e32 v13, v14
	v_lshl_add_u64 v[0:1], v[0:1], 2, v[8:9]
	v_lshl_add_u64 v[4:5], v[2:3], 2, v[8:9]
	v_lshl_add_u64 v[10:11], v[10:11], 2, v[8:9]
	v_lshl_add_u64 v[12:13], v[12:13], 2, v[8:9]
	global_load_dwordx4 v[0:3], v[0:1], off nt
	s_nop 0
	global_load_dwordx4 v[4:7], v[4:5], off nt
	s_nop 0
	global_load_dwordx4 v[8:11], v[10:11], off nt
	s_nop 0
	global_load_dwordx4 v[12:15], v[12:13], off nt
	s_add_i32 s3, 0, 0x10000
	v_lshrrev_b32_e32 v19, 1, v20
	s_movk_i32 s4, 0x104
	v_lshlrev_b32_e32 v16, 2, v17
	v_add_u32_e32 v18, s3, v152
	v_lshlrev_b32_e32 v31, 3, v17
	v_mul_u32_u24_e32 v17, 0x820, v17
	v_and_b32_e32 v33, 12, v19
	v_mul_lo_u32 v19, v20, s4
	v_lshlrev_b32_e32 v28, 2, v20
	v_and_b32_e32 v32, 15, v20
	v_bfe_u32 v34, v48, 2, 1
	v_and_b32_e32 v35, 48, v152
	v_add3_u32 v36, s3, v17, v28
	v_add_u32_e32 v37, v18, v19
	v_lshlrev_b32_e32 v28, 2, v16
	s_mov_b32 s14, s20
	s_mov_b32 s13, s19
	s_mov_b32 s12, s18
	s_mov_b64 s[4:5], s[0:1]
	s_waitcnt vmcnt(0)
	s_branch .LBB0_360

; #define LAS __attribute__((address_space(3)))
; __device__ __forceinline__ void pro_a_phase(const Params& p, LAS unsigned char* lds) {
;     ...
;     auto decode = [&](int tt, const float*& src, bf16_t*& dst, int& K, int& N, int& mode, int& n0, int& k0) {
;         const int l = tt / 6144, u = tt % 6144; int v;
;         if (u < 1536) { mode = 2; K = DM; N = DIN; v = u; src = p.w_in + (size_t)l * DM * DIN; dst = (bf16_t*)(p.ws + WS_WT_IN) + (size_t)l * DIN * LDU; }
;         else if (u < 2048) { mode = 1; K = DM; N = DM; v = u - 1536; src = p.w_out + (size_t)l * DM * DM; dst = (bf16_t*)(p.ws + WS_WT_OUT) + (size_t)l * DM * LDU; }
;         else if (u < 4096) { mode = 1; K = DM; N = DFF; v = u - 2048; src = p.w_ff1 + (size_t)l * DM * DFF; dst = (bf16_t*)(p.ws + WS_WT_FF1) + (size_t)l * DFF * LDU; }
;         else { mode = 1; K = DFF; N = DM; v = u - 4096; src = p.w_ff2 + (size_t)l * DFF * DM; dst = (bf16_t*)(p.ws + WS_WT_FF2) + (size_t)l * DM * LDH; }
;     ...
;         for (;;) {
; #pragma unroll
;             for (int i = 0; i < 4; ++i) { LAS float* tp = tile + (lk + 32 * i) * 65 + ln4 * 4; tp[0] = rg[i][0]; tp[1] = rg[i][1]; tp[2] = rg[i][2]; tp[3] = rg[i][3]; }
;             asm volatile("s_waitcnt lgkmcnt(0)" ::: "memory"); __builtin_amdgcn_s_barrier(); asm volatile("" ::: "memory");
;             bf16_t* cdst = dst; const int cnkt = K >> 6, cmode = mode, cn0 = n0, ck0 = k0;
;             const int tn = tt + G;
;             if (tn < N_TR) { decode(tn, src, dst, K, N, mode, n0, k0);
.LBB0_360:
	v_add_u32_e32 v16, 0x2080, v37
	s_waitcnt vmcnt(2)
	ds_write2_b32 v37, v0, v1 offset1:1
	ds_write2_b32 v37, v2, v3 offset0:2 offset1:3
	ds_write2_b32 v16, v4, v5 offset1:1
	v_add_u32_e32 v16, 0x2088, v37
	ds_write2_b32 v16, v6, v7 offset1:1
	v_add_u32_e32 v16, 0x4100, v37
	ds_write2_b32 v16, v8, v9 offset1:1
	v_add_u32_e32 v16, 0x4108, v37
	ds_write2_b32 v16, v10, v11 offset1:1
	v_add_u32_e32 v16, 0x6180, v37
	ds_write2_b32 v16, v12, v13 offset1:1
	v_add_u32_e32 v16, 0x6188, v37
	ds_write2_b32 v16, v14, v15 offset1:1
	s_waitcnt lgkmcnt(0)
	s_barrier
	s_waitcnt lgkmcnt(0)
	s_add_i32 s17, s17, s16
	s_cmpk_gt_i32 s17, 0x2fff
	s_mov_b32 s6, s2
	s_cbranch_scc1 .LBB0_373
	s_mul_hi_i32 s3, s17, 0x2aaaaaab
	s_lshr_b32 s4, s3, 31
	s_ashr_i32 s3, s3, 10
	s_add_i32 s6, s3, s4
	s_mul_i32 s3, s6, 0xffffe800
	s_add_i32 s3, s17, s3
	s_cmpk_gt_i32 s3, 0x5ff
	s_mov_b64 s[10:11], -1
	s_cbranch_scc0 .LBB0_370
	s_mul_i32 s4, s6, 0x1800
	s_sub_i32 s22, s17, s4
	s_ashr_i32 s7, s6, 31
	s_cmpk_gt_u32 s3, 0x7ff
	s_cbranch_scc0 .LBB0_367
	s_lshl_b64 s[12:13], s[6:7], 26
	s_lshl_b64 s[10:11], s[6:7], 25
	s_cmpk_gt_u32 s3, 0xfff
	s_mov_b64 s[14:15], -1
	s_cbranch_scc0 .LBB0_365
	s_add_i32 s21, s22, 0xfffff000
	s_add_u32 s8, s70, s12
	s_addc_u32 s9, s71, s13
	v_readlane_b32 s4, v252, 59
	s_add_u32 s4, s4, s10
	v_readlane_b32 s5, v252, 60
	s_addc_u32 s5, s5, s11
	s_mov_b64 s[14:15], 0
